# helpers moved to the START of P1 / P8 for the 64 short WGs (10240 P0-list tiles, 10752 down2 tiles), alternating P5 queue
# baseline (speedup 1.0000x reference)
; #define LAS __attribute__((address_space(3)))
; #define REFRESH_IDS() do { lane = fresh_lane(); tid = wave * 64 + lane; } while (0)
; __global__ void __launch_bounds__(NWAVES * 64, 2) fwd(Args args) {
;     ...
;     if (IN(0)) {
;         REFRESH_IDS();
;         LAS float* scr = (LAS float*)(L + wave * (64 * 65 * 4));
;         const int NS0 = ((NI0 / 32 * 27) / NGW) * NGW;
;         P0_RUN(gw, NS0, NGW);
.LBB0_8:
	s_or_b64 exec, exec, s[4:5]
	s_lshl_b32 s4, s75, 3
	s_add_i32 s16, s4, s28
	s_lshl_b32 s18, s33, 3
	s_add_u32 s6, s14, 0x40000
	s_addc_u32 s7, s15, 0
	s_add_u32 s36, s14, 0x400000
	s_addc_u32 s37, s15, 0
	s_add_u32 s34, s14, 0xb400000
	s_addc_u32 s35, s15, 0
	s_load_dwordx2 s[96:97], s[0:1], 0x98
	s_add_u32 s10, s14, 0x10c00000
	s_addc_u32 s11, s15, 0
	s_add_u32 s26, s14, 0x2a800000
	s_addc_u32 s27, s15, 0
	s_waitcnt lgkmcnt(0)
	s_cmp_lt_i32 s96, 1
	s_cselect_b64 s[4:5], -1, 0
	s_cmp_gt_i32 s97, 0
	s_cselect_b64 s[20:21], -1, 0
	s_and_b64 s[4:5], s[4:5], s[20:21]
	s_and_b64 vcc, exec, s[4:5]
	s_mul_i32 s74, s28, 0x4100
	s_cbranch_vccz .LBB0_219
	s_abs_i32 s4, s18
	v_cvt_f32_u32_e32 v0, s4
	s_sub_i32 s5, 0, s4
	s_add_i32 s19, s74, 0
	v_mbcnt_lo_u32_b32 v140, -1, 0
	v_mbcnt_hi_u32_b32 v140, -1, v140
	v_rcp_iflag_f32_e32 v0, v0
	s_nop 0
	v_mul_f32_e32 v0, 0x4f7ffffe, v0
	v_cvt_u32_f32_e32 v0, v0
	s_nop 0
	v_readfirstlane_b32 s17, v0
	s_mul_i32 s5, s5, s17
	s_mul_hi_u32 s5, s17, s5
	s_add_i32 s17, s17, s5
	s_mul_hi_u32 s5, s17, 0x744e
	s_mul_i32 s5, s5, s4
	s_sub_i32 s5, 0x744e, s5
	s_sub_i32 s17, s5, s4
	s_cmp_ge_u32 s5, s4
	s_cselect_b32 s5, s17, s5
	s_sub_i32 s17, s5, s4
	s_cmp_ge_u32 s5, s4
	s_cselect_b32 s23, s17, s5
	s_sub_i32 s22, 0x744e, s23
	s_cmp_ge_i32 s16, s22
	s_cbranch_scc1 .LBB0_84
	s_cmpk_gt_i32 s16, 0x55ff
	s_cbranch_scc0 .LBB0_14
	s_cmpk_gt_u32 s16, 0x80ff
	s_cbranch_scc0 .LBB0_15
	s_add_u32 s42, s0, 48
	s_addc_u32 s43, s1, 0
	s_add_i32 s17, s16, 0x7f00
	s_and_b32 s20, s17, 0xffff
	s_mul_i32 s20, s20, 0x91a3
	s_load_dwordx2 s[4:5], s[0:1], 0x28
	s_lshr_b32 s20, s20, 23
	s_lshl_b32 s30, s20, 6
	s_mulk_i32 s20, 0xe1
	s_sub_i32 s17, s17, s20
	s_lshl_b32 s17, s17, 6
	s_and_b32 s17, s17, 0xffc0
	s_cbranch_execz .LBB0_16
	s_movk_i32 s25, 0x1040
	s_movk_i32 s24, 0x3820
	s_mov_b64 s[40:41], s[10:11]
	s_branch .LBB0_17

; #define LDS_BAR() do { asm volatile("s_waitcnt lgkmcnt(0)" ::: "memory"); __builtin_amdgcn_s_barrier(); asm volatile("" ::: "memory"); } while (0)
; #define LAS __attribute__((address_space(3)))
; #define REFRESH_IDS() do { lane = fresh_lane(); tid = wave * 64 + lane; } while (0)
; __global__ void __launch_bounds__(NWAVES * 64, 2) fwd(Args args) {
;     ...
;           for (unsigned it = 0u;; ++it) {
;               LDS_BAR();
;               const unsigned q = MISC[16 + (it & 1u)]; if (q >= NTB) break;
;               if (tid == 0) { int z = 0; asm volatile("" : "+v"(z)); qpre = __hip_atomic_fetch_add(ctl + CW_AQ + 64 + z, 1u, __ATOMIC_RELAXED, __HIP_MEMORY_SCOPE_AGENT); }
;               volatile LAS unsigned* qslot = MISC + 16 + ((it + 1u) & 1u);
;               REFRESH_IDS();
;               int t0 = NS0 + (int)q * 16 + wave, t1 = t0 + 8; t0 = t0 < NI0 - 1 ? t0 : NI0 - 1; t1 = t1 < NI0 - 1 ? t1 : NI0 - 1;
;               f32x4 va[16], vb[16]; P0T_DECL(a); P0T_DECL(b);
;               P0T_RESOLVE(a, t0); p0_load(aW, aN, ak0, an0, lane, va);
.LBB0_103:
	s_or_b64 exec, exec, s[46:47]
	s_lshl_b32 s23, s23, 4
	s_add_i32 s23, s20, s23
	s_min_i32 s24, s23, 0x913f
	s_cmpk_gt_u32 s23, 0x55ff
	v_mbcnt_lo_u32_b32 v140, -1, 0
	v_mbcnt_hi_u32_b32 v140, -1, v140
	s_cbranch_scc0 .LBB0_108
	s_cmpk_gt_u32 s23, 0x80ff
	s_mov_b64 s[46:47], -1
	s_cbranch_scc0 .LBB0_106
	s_add_i32 s25, s24, 0xffff7f00
	s_mul_hi_u32 s29, s25, 0x91a2b3c5
	s_lshr_b32 s29, s29, 7
	s_lshl_b32 s56, s29, 6
	s_mulk_i32 s29, 0xe1
	s_sub_i32 s25, s25, s29
	s_lshl_b32 s67, s25, 6
	s_mov_b64 s[46:47], 0
	s_mov_b64 s[60:61], s[40:41]

; __device__ __forceinline__ void p0_load(const float* W, int N, int k0, int n0, int lane, f32x4 (&v)[16]) {
;     const int c = lane & 15, rq = lane >> 4;
;     int col = n0 + 4 * c; col = col < N - 4 ? col : N - 4;
;     const float* p = W + (size_t)(k0 + rq) * N + col;
; #pragma unroll
;     for (int j = 0; j < 16; ++j) v[j] = __builtin_nontemporal_load((const f32x4*)(p + (size_t)(4 * j) * N));
; __global__ void __launch_bounds__(NWAVES * 64, 2) fwd(Args args) {
;     ...
;               int t0 = NS0 + (int)q * 16 + wave, t1 = t0 + 8; t0 = t0 < NI0 - 1 ? t0 : NI0 - 1; t1 = t1 < NI0 - 1 ? t1 : NI0 - 1;
;               f32x4 va[16], vb[16]; P0T_DECL(a); P0T_DECL(b);
;               P0T_RESOLVE(a, t0); p0_load(aW, aN, ak0, an0, lane, va);
;               P0T_RESOLVE(b, t1); p0_load(bW, bN, bk0, bn0, lane, vb);
.LBB0_112:
	v_ashrrev_i32_e32 v142, 4, v140
	s_load_dwordx2 s[24:25], s[46:47], 0x0
	v_add_u32_e32 v1, s56, v142
	v_lshlrev_b32_e32 v0, 2, v140
	v_mad_u64_u32 v[2:3], s[46:47], v1, s68, 0
	v_and_b32_e32 v143, 60, v0
	v_ashrrev_i32_e32 v5, 31, v1
	v_mov_b32_e32 v4, v3
	v_or_b32_e32 v0, s67, v143
	s_add_i32 s29, s68, -4
	v_mad_u64_u32 v[4:5], s[46:47], v5, s68, v[4:5]
	v_min_i32_e32 v0, s29, v0
	v_mov_b32_e32 v3, v4
	s_waitcnt lgkmcnt(0)
	v_lshl_add_u64 v[2:3], v[2:3], 2, s[24:25]
	v_ashrrev_i32_e32 v1, 31, v0
	v_lshl_add_u64 v[0:1], v[0:1], 2, v[2:3]
	s_lshl_b32 s44, s68, 2
	v_lshl_add_u64 v[2:3], s[44:45], 2, v[0:1]
	s_lshl_b32 s44, s68, 3
	global_load_dwordx4 v[76:79], v[0:1], off nt
	global_load_dwordx4 v[72:75], v[2:3], off nt
	v_lshl_add_u64 v[2:3], s[44:45], 2, v[0:1]
	s_mul_i32 s44, s68, 12
	v_lshl_add_u64 v[4:5], s[44:45], 2, v[0:1]
	s_lshl_b32 s44, s68, 4
	global_load_dwordx4 v[84:87], v[2:3], off nt
	global_load_dwordx4 v[80:83], v[4:5], off nt
	v_lshl_add_u64 v[2:3], s[44:45], 2, v[0:1]
	s_mul_i32 s44, s68, 20
	v_lshl_add_u64 v[4:5], s[44:45], 2, v[0:1]
	s_mul_i32 s44, s68, 24
	global_load_dwordx4 v[92:95], v[2:3], off nt
	global_load_dwordx4 v[88:91], v[4:5], off nt
	v_lshl_add_u64 v[2:3], s[44:45], 2, v[0:1]
	s_mul_i32 s44, s68, 28
	v_lshl_add_u64 v[4:5], s[44:45], 2, v[0:1]
	s_lshl_b32 s44, s68, 5
	global_load_dwordx4 v[100:103], v[2:3], off nt
	global_load_dwordx4 v[96:99], v[4:5], off nt
	v_lshl_add_u64 v[2:3], s[44:45], 2, v[0:1]
	s_mul_i32 s44, s68, 36
	v_lshl_add_u64 v[4:5], s[44:45], 2, v[0:1]
	s_mul_i32 s44, s68, 40
	global_load_dwordx4 v[108:111], v[2:3], off nt
	global_load_dwordx4 v[104:107], v[4:5], off nt
	v_lshl_add_u64 v[2:3], s[44:45], 2, v[0:1]
	s_mul_i32 s44, s68, 44
	v_lshl_add_u64 v[4:5], s[44:45], 2, v[0:1]
	s_mul_i32 s44, s68, 48
	global_load_dwordx4 v[116:119], v[2:3], off nt
	global_load_dwordx4 v[112:115], v[4:5], off nt
	v_lshl_add_u64 v[2:3], s[44:45], 2, v[0:1]
	s_mul_i32 s44, s68, 52
	v_lshl_add_u64 v[4:5], s[44:45], 2, v[0:1]
	s_mul_i32 s44, s68, 56
	global_load_dwordx4 v[124:127], v[2:3], off nt
	global_load_dwordx4 v[120:123], v[4:5], off nt
	v_lshl_add_u64 v[2:3], s[44:45], 2, v[0:1]
	s_mul_i32 s44, s68, 60
	v_lshl_add_u64 v[0:1], s[44:45], 2, v[0:1]
	global_load_dwordx4 v[132:135], v[2:3], off nt
	global_load_dwordx4 v[128:131], v[0:1], off nt
	s_min_i32 s25, s23, 0x9137
	s_cmpk_gt_u32 s23, 0x55f7
	s_cbranch_scc0 .LBB0_117
	s_cmpk_gt_u32 s23, 0x80f7
	s_mov_b64 s[46:47], -1
	s_cbranch_scc0 .LBB0_115
	s_add_i32 s23, s25, 0xffff7f08
	s_mul_hi_u32 s24, s23, 0x91a2b3c5
	s_lshr_b32 s24, s24, 7
	s_lshl_b32 s50, s24, 6
	s_mulk_i32 s24, 0xe1
	s_sub_i32 s23, s23, s24
	s_lshl_b32 s23, s23, 6
	s_mov_b64 s[46:47], 0
	s_mov_b64 s[54:55], s[40:41]

; #define REFRESH_IDS() do { lane = fresh_lane(); tid = wave * 64 + lane; } while (0)
; __global__ void __launch_bounds__(NWAVES * 64, 2) fwd(Args args) {
;     ...
;     if (IN(1)) {
;         REFRESH_IDS();
;         pg8::Gemm g{XB, Wgu1, M, 2 * FF, D, LDD, LDD}; pg8::StaticOrder S; S.init(M, 2 * FF, G, bx);
;         pg8::EpiGateUp E{ACT, ssq};
;         pg8::gemm_phase<pg8::EpiGateUp, pg8::StaticOrder, true, true>(L, g, S, E, wave);
.LBB0_219:
	s_add_u32 s30, s14, 0x2ea00000
	s_addc_u32 s31, s15, 0
	s_cmp_lt_i32 s96, 2
	s_cselect_b64 s[2:3], -1, 0
	s_cmp_gt_i32 s97, 1
	s_cselect_b64 s[4:5], -1, 0
	s_and_b64 s[2:3], s[2:3], s[4:5]
	s_andn2_b64 vcc, exec, s[2:3]
	s_cbranch_vccnz .LBB0_296
	s_cmpk_lt_u32 s8, 0xc0
	s_cbranch_scc1 .Lha_done
	v_writelane_b32 v238, s0, 0
	v_writelane_b32 v238, s1, 1
	v_writelane_b32 v238, s2, 2
	v_writelane_b32 v238, s3, 3
	v_writelane_b32 v238, s4, 4
	v_writelane_b32 v238, s5, 5
	v_writelane_b32 v238, s6, 6
	v_writelane_b32 v238, s7, 7
	v_writelane_b32 v238, s8, 8
	v_writelane_b32 v238, s9, 9
	v_writelane_b32 v238, s10, 10
	v_writelane_b32 v238, s11, 11
	v_writelane_b32 v238, s12, 12
	v_writelane_b32 v238, s13, 13
	v_writelane_b32 v238, s14, 14
	v_writelane_b32 v238, s15, 15
	v_writelane_b32 v238, s16, 16
	v_writelane_b32 v238, s17, 17
	v_writelane_b32 v238, s18, 18
	v_writelane_b32 v238, s19, 19
	v_writelane_b32 v238, s20, 20
	v_writelane_b32 v238, s21, 21
	v_writelane_b32 v238, s22, 22
	v_writelane_b32 v238, s23, 23
	v_writelane_b32 v238, s24, 24
	v_writelane_b32 v238, s25, 25
	v_writelane_b32 v238, s26, 26
	v_writelane_b32 v238, s27, 27
	v_writelane_b32 v238, s28, 28
	v_writelane_b32 v238, s29, 29
	v_writelane_b32 v238, s30, 30
	v_writelane_b32 v238, s31, 31
	v_writelane_b32 v238, s32, 32
	v_writelane_b32 v238, s33, 33
	v_writelane_b32 v238, s34, 34
	v_writelane_b32 v238, s35, 35
	v_writelane_b32 v238, s36, 36
	v_writelane_b32 v238, s37, 37
	v_writelane_b32 v238, s38, 38
	v_writelane_b32 v238, s39, 39
	v_writelane_b32 v238, s40, 40
	v_writelane_b32 v238, s41, 41
	v_writelane_b32 v238, s42, 42
	v_writelane_b32 v238, s43, 43
	v_writelane_b32 v238, s44, 44
	v_writelane_b32 v238, s45, 45
	v_writelane_b32 v238, s46, 46
	v_writelane_b32 v238, s47, 47
	v_writelane_b32 v238, s48, 48
	v_writelane_b32 v238, s49, 49
	v_writelane_b32 v238, s50, 50
	v_writelane_b32 v238, s51, 51
	v_writelane_b32 v238, s52, 52
	v_writelane_b32 v238, s53, 53
	v_writelane_b32 v238, s54, 54
	v_writelane_b32 v238, s55, 55
	v_writelane_b32 v238, s56, 56
	v_writelane_b32 v238, s57, 57
	v_writelane_b32 v238, s58, 58
	v_writelane_b32 v238, s59, 59
	v_writelane_b32 v238, s60, 60
	v_writelane_b32 v238, s61, 61
	v_writelane_b32 v238, s62, 62
	v_writelane_b32 v238, s63, 63
	v_writelane_b32 v239, s64, 0
	v_writelane_b32 v239, s65, 1
	v_writelane_b32 v239, s66, 2
	v_writelane_b32 v239, s67, 3
	v_writelane_b32 v239, s68, 4
	v_writelane_b32 v239, s69, 5
	v_writelane_b32 v239, s70, 6
	v_writelane_b32 v239, s71, 7
	v_writelane_b32 v239, s72, 8
	v_writelane_b32 v239, s73, 9
	v_writelane_b32 v239, s74, 10
	v_writelane_b32 v239, s75, 11
	v_writelane_b32 v239, s76, 12
	v_writelane_b32 v239, s77, 13
	v_writelane_b32 v239, s78, 14
	v_writelane_b32 v239, s79, 15
	v_writelane_b32 v239, s80, 16
	v_writelane_b32 v239, s81, 17
	v_writelane_b32 v239, s82, 18
	v_writelane_b32 v239, s83, 19
	v_writelane_b32 v239, s84, 20
	v_writelane_b32 v239, s85, 21
	v_writelane_b32 v239, s86, 22
	v_writelane_b32 v239, s87, 23
	v_writelane_b32 v239, s88, 24
	v_writelane_b32 v239, s89, 25
	v_writelane_b32 v239, s90, 26
	v_writelane_b32 v239, s91, 27
	v_writelane_b32 v239, s92, 28
	v_writelane_b32 v239, s93, 29
	v_writelane_b32 v239, s94, 30
	v_writelane_b32 v239, s95, 31
	v_writelane_b32 v239, s96, 32
	v_writelane_b32 v239, s97, 33
	v_writelane_b32 v239, s98, 34
	v_writelane_b32 v239, s99, 35
	v_writelane_b32 v239, s100, 36
	v_writelane_b32 v239, s101, 37
	v_writelane_b32 v239, vcc_lo, 38
	v_writelane_b32 v239, vcc_hi, 39
	v_writelane_b32 v239, m0, 40
	s_add_i32 s75, s8, 0xffffff40
	s_mov_b32 s33, 64
	s_lshl_b32 s9, s28, 6
	s_lshl_b32 s4, s75, 3
	s_add_i32 s16, s4, s28
	s_lshl_b32 s18, s33, 3
	s_add_u32 s6, s14, 0x40000
	s_addc_u32 s7, s15, 0
	s_add_u32 s36, s14, 0x400000
	s_addc_u32 s37, s15, 0
	s_add_u32 s34, s14, 0xb400000
	s_addc_u32 s35, s15, 0
	s_load_dwordx2 s[96:97], s[0:1], 0x98
	s_add_u32 s10, s14, 0x10c00000
	s_addc_u32 s11, s15, 0
	s_add_u32 s26, s14, 0x2a800000
	s_addc_u32 s27, s15, 0
	s_waitcnt lgkmcnt(0)
	s_cmp_lt_i32 s96, 1
	s_cselect_b64 s[4:5], -1, 0
	s_cmp_gt_i32 s97, 0
	s_cselect_b64 s[20:21], -1, 0
	s_and_b64 s[4:5], s[4:5], s[20:21]
	s_and_b64 vcc, exec, s[4:5]
	s_mul_i32 s74, s28, 0x4100
	s_cbranch_vccz .Lha_end
	s_abs_i32 s4, s18
	v_cvt_f32_u32_e32 v0, s4
	s_sub_i32 s5, 0, s4
	s_add_i32 s19, s74, 0
	v_mbcnt_lo_u32_b32 v140, -1, 0
	v_mbcnt_hi_u32_b32 v140, -1, v140
	v_rcp_iflag_f32_e32 v0, v0
	s_nop 0
	v_mul_f32_e32 v0, 0x4f7ffffe, v0
	v_cvt_u32_f32_e32 v0, v0
	s_nop 0
	v_readfirstlane_b32 s17, v0
	s_mul_i32 s5, s5, s17
	s_mul_hi_u32 s5, s17, s5
	s_add_i32 s17, s17, s5
	s_mul_hi_u32 s5, s17, 0x9c4e
	s_mul_i32 s5, s5, s4
	s_sub_i32 s5, 0x9c4e, s5
	s_sub_i32 s17, s5, s4
	s_cmp_ge_u32 s5, s4
	s_cselect_b32 s5, s17, s5
	s_sub_i32 s17, s5, s4
	s_cmp_ge_u32 s5, s4
	s_cselect_b32 s23, s17, s5
	s_sub_i32 s22, 0x9c4e, s23
	s_add_i32 s16, s16, 0x9140
	s_mov_b32 s22, 0xb940
	s_cmp_ge_i32 s16, s22
	s_cbranch_scc1 .Lha_end
	s_cmpk_gt_i32 s16, 0x55ff
	s_cbranch_scc0 .Lha_14
	s_cmpk_gt_u32 s16, 0x80ff
	s_cbranch_scc0 .Lha_15
	s_add_u32 s42, s0, 48
	s_addc_u32 s43, s1, 0
	s_add_i32 s17, s16, 0x7f00
	s_and_b32 s20, s17, 0xffff
	s_mul_i32 s20, s20, 0x91a3
	s_load_dwordx2 s[4:5], s[0:1], 0x28
	s_lshr_b32 s20, s20, 23
	s_lshl_b32 s30, s20, 6
	s_mulk_i32 s20, 0xe1
	s_sub_i32 s17, s17, s20
	s_lshl_b32 s17, s17, 6
	s_and_b32 s17, s17, 0xffc0
	s_cbranch_execz .Lha_16
	s_movk_i32 s25, 0x1040
	s_movk_i32 s24, 0x3820
	s_mov_b64 s[40:41], s[10:11]
	s_branch .Lha_17

; #define REFRESH_IDS() do { lane = fresh_lane(); tid = wave * 64 + lane; } while (0)
; __global__ void __launch_bounds__(NWAVES * 64, 2) fwd(Args args) {
;     ...
;     if (IN(1)) {
;         REFRESH_IDS();
;         pg8::Gemm g{XB, Wgu1, M, 2 * FF, D, LDD, LDD}; pg8::StaticOrder S; S.init(M, 2 * FF, G, bx);
;         pg8::EpiGateUp E{ACT, ssq};
;         pg8::gemm_phase<pg8::EpiGateUp, pg8::StaticOrder, true, true>(L, g, S, E, wave);
.Lha_end:
	s_waitcnt vmcnt(0) lgkmcnt(0)
	v_readlane_b32 s2, v239, 40
	s_mov_b32 m0, s2
	v_readlane_b32 s0, v238, 0
	v_readlane_b32 s1, v238, 1
	v_readlane_b32 s2, v238, 2
	v_readlane_b32 s3, v238, 3
	v_readlane_b32 s4, v238, 4
	v_readlane_b32 s5, v238, 5
	v_readlane_b32 s6, v238, 6
	v_readlane_b32 s7, v238, 7
	v_readlane_b32 s8, v238, 8
	v_readlane_b32 s9, v238, 9
	v_readlane_b32 s10, v238, 10
	v_readlane_b32 s11, v238, 11
	v_readlane_b32 s12, v238, 12
	v_readlane_b32 s13, v238, 13
	v_readlane_b32 s14, v238, 14
	v_readlane_b32 s15, v238, 15
	v_readlane_b32 s16, v238, 16
	v_readlane_b32 s17, v238, 17
	v_readlane_b32 s18, v238, 18
	v_readlane_b32 s19, v238, 19
	v_readlane_b32 s20, v238, 20
	v_readlane_b32 s21, v238, 21
	v_readlane_b32 s22, v238, 22
	v_readlane_b32 s23, v238, 23
	v_readlane_b32 s24, v238, 24
	v_readlane_b32 s25, v238, 25
	v_readlane_b32 s26, v238, 26
	v_readlane_b32 s27, v238, 27
	v_readlane_b32 s28, v238, 28
	v_readlane_b32 s29, v238, 29
	v_readlane_b32 s30, v238, 30
	v_readlane_b32 s31, v238, 31
	v_readlane_b32 s32, v238, 32
	v_readlane_b32 s33, v238, 33
	v_readlane_b32 s34, v238, 34
	v_readlane_b32 s35, v238, 35
	v_readlane_b32 s36, v238, 36
	v_readlane_b32 s37, v238, 37
	v_readlane_b32 s38, v238, 38
	v_readlane_b32 s39, v238, 39
	v_readlane_b32 s40, v238, 40
	v_readlane_b32 s41, v238, 41
	v_readlane_b32 s42, v238, 42
	v_readlane_b32 s43, v238, 43
	v_readlane_b32 s44, v238, 44
	v_readlane_b32 s45, v238, 45
	v_readlane_b32 s46, v238, 46
	v_readlane_b32 s47, v238, 47
	v_readlane_b32 s48, v238, 48
	v_readlane_b32 s49, v238, 49
	v_readlane_b32 s50, v238, 50
	v_readlane_b32 s51, v238, 51
	v_readlane_b32 s52, v238, 52
	v_readlane_b32 s53, v238, 53
	v_readlane_b32 s54, v238, 54
	v_readlane_b32 s55, v238, 55
	v_readlane_b32 s56, v238, 56
	v_readlane_b32 s57, v238, 57
	v_readlane_b32 s58, v238, 58
	v_readlane_b32 s59, v238, 59
	v_readlane_b32 s60, v238, 60
	v_readlane_b32 s61, v238, 61
	v_readlane_b32 s62, v238, 62
	v_readlane_b32 s63, v238, 63
	v_readlane_b32 s64, v239, 0
	v_readlane_b32 s65, v239, 1
	v_readlane_b32 s66, v239, 2
	v_readlane_b32 s67, v239, 3
	v_readlane_b32 s68, v239, 4
	v_readlane_b32 s69, v239, 5
	v_readlane_b32 s70, v239, 6
	v_readlane_b32 s71, v239, 7
	v_readlane_b32 s72, v239, 8
	v_readlane_b32 s73, v239, 9
	v_readlane_b32 s74, v239, 10
	v_readlane_b32 s75, v239, 11
	v_readlane_b32 s76, v239, 12
	v_readlane_b32 s77, v239, 13
	v_readlane_b32 s78, v239, 14
	v_readlane_b32 s79, v239, 15
	v_readlane_b32 s80, v239, 16
	v_readlane_b32 s81, v239, 17
	v_readlane_b32 s82, v239, 18
	v_readlane_b32 s83, v239, 19
	v_readlane_b32 s84, v239, 20
	v_readlane_b32 s85, v239, 21
	v_readlane_b32 s86, v239, 22
	v_readlane_b32 s87, v239, 23
	v_readlane_b32 s88, v239, 24
	v_readlane_b32 s89, v239, 25
	v_readlane_b32 s90, v239, 26
	v_readlane_b32 s91, v239, 27
	v_readlane_b32 s92, v239, 28
	v_readlane_b32 s93, v239, 29
	v_readlane_b32 s94, v239, 30
	v_readlane_b32 s95, v239, 31
	v_readlane_b32 s96, v239, 32
	v_readlane_b32 s97, v239, 33
	v_readlane_b32 s98, v239, 34
	v_readlane_b32 s99, v239, 35
	v_readlane_b32 s100, v239, 36
	v_readlane_b32 s101, v239, 37
	v_readlane_b32 vcc_lo, v239, 38
	v_readlane_b32 vcc_hi, v239, 39
	s_barrier
; __device__ __forceinline__ int fresh_lane() { int l; asm volatile("v_mbcnt_lo_u32_b32 %0, -1, 0\n\tv_mbcnt_hi_u32_b32 %0, -1, %0" : "=v"(l)); return l; }
;     __host__ __device__ bool next(int i, Unit& u) const { return map((long)i * G + c, u); }
;     __host__ __device__ bool next(int i, Unit& u) const { if (i > 0) return false; const int x = c & 7, j = c >> 3; u.pm = 16 * s + 4 * (x >> 1) + (j & 3); u.pn = 8 * (x & 1) + (j >> 2); return true; }
; #define PG8_WAIT_V(n) asm volatile("s_waitcnt vmcnt(" #n ")" ::: "memory")
; template <class Epi, class Sched, bool ALIGN_EPI = false, bool SP2 = false>
; __device__ __forceinline__ void gemm_phase(PG8_LAS unsigned char* lds, const Gemm g, const Sched& S, const Epi& E, int wid) {
;     const int lane = fresh_lane(), tid = wid * 64 + lane, wr = wid >> 2, wc = wid & 3, fr = lane & 15, fq = lane >> 4;
;     const int K = g.K, nt = K / BK;
;     unsigned voffA[2], voffB[2];
; #pragma unroll
;     for (int i = 0; i < 2; ++i) { int R, C; stage_rc(tid * 16 + i * 8192, R, C); const int Rb = Epi::PERM ? ((R & ~31) + perm32(R & 31)) : R;
;         voffA[i] = (unsigned)(R * g.lda + C) * 2u; voffB[i] = (unsigned)(Rb * g.ldb + C) * 2u; }
;     const size_t kstep = (size_t)(BK * 2);
;     const size_t hstepA = (size_t)HALF * g.lda * 2, hstepB = (size_t)HALF * g.ldb * 2;
;     const size_t tstepA = 2 * hstepA, tstepB = 2 * hstepB;
;     const unsigned ldsw = (unsigned)wid * 1024u;
;     const int aoff = lds_byte(wr * 64 + fr, fq * 8), boff = lds_byte(wc * 32 + fr, fq * 8);
;     ...
;     Unit cur, nxt; int ui = 0;
;     if (!S.next(0, cur)) return;
;     f32x4 acc[2][2][4][2];
; #pragma unroll
;     for (int a = 0; a < 2; ++a)
; #pragma unroll
;         for (int b = 0; b < 2; ++b)
; #pragma unroll
;             for (int m = 0; m < 4; ++m)
; #pragma unroll
;                 for (int n = 0; n < 2; ++n) acc[a][b][m][n] = (f32x4){0.f, 0.f, 0.f, 0.f};
;     bf16x8 At[4][2], B0[2][2], B1[2][2];
;     const char* cA = (const char*)g.A + (size_t)cur.pm * tstepA; const char* cB = (const char*)g.Bt + (size_t)cur.pn * tstepB;
;     S.a_ready(cur);
;     if constexpr (SP2) {
;         PG8_STAGE_NT(PG8_SB(0, 0), cB, voffB); PG8_STAGE_NT(PG8_SB(0, 1), cB + hstepB, voffB); PG8_STAGE(PG8_SA(0, 0), cA, voffA); PG8_STAGE(PG8_SA(0, 1), cA + hstepA, voffA);
;         if (wr == 1) PG8_BAR;
;         PG8_WAIT_V(2); PG8_BAR;
.Lha_done:
	s_cmpk_gt_i32 s8, 0xabf
	v_mbcnt_lo_u32_b32 v0, -1, 0
	v_mbcnt_hi_u32_b32 v0, -1, v0
	v_mbcnt_lo_u32_b32 v10, -1, 0
	v_mbcnt_hi_u32_b32 v10, -1, v10
	s_cbranch_scc1 .LBB0_240
	s_lshl_b32 s17, s28, 10
	v_lshl_add_u32 v0, v10, 4, s17
	v_add_u32_e32 v1, 0x2000, v0
	v_ashrrev_i32_e32 v2, 31, v1
	v_lshrrev_b32_e32 v2, 22, v2
	v_add_u32_e32 v2, v1, v2
	v_ashrrev_i32_e32 v8, 10, v2
	v_mul_i32_i24_e32 v2, 0x400, v8
	v_sub_u32_e32 v1, v1, v2
	v_lshrrev_b32_e32 v2, 4, v1
	v_bitop3_b32 v1, v2, v1, 32 bitop3:0x6c
	v_ashrrev_i32_e32 v2, 31, v1
	v_lshrrev_b32_e32 v2, 26, v2
	v_add_u32_e32 v2, v1, v2
	v_ashrrev_i32_e32 v9, 6, v2
	v_lshlrev_b32_e32 v3, 3, v8
	v_and_b32_e32 v2, 0xffc0, v2
	v_and_b32_e32 v3, -16, v3
	v_sub_u32_e32 v1, v1, v2
	v_add_u32_e32 v3, v9, v3
	v_lshrrev_b16_e32 v2, 7, v1
	v_and_b32_e32 v4, 3, v9
	s_mov_b32 s4, 0x3ffffe0
	v_lshrrev_b32_e32 v5, 2, v3
	v_lshlrev_b32_e32 v6, 1, v3
	v_and_b32_e32 v2, 1, v2
	v_and_or_b32 v4, v3, s4, v4
	v_and_b32_e32 v5, 4, v5
	v_and_b32_e32 v6, 24, v6
	v_add_u16_e32 v1, v1, v2
	v_mov_b32_e32 v2, 1
	v_or3_b32 v4, v4, v5, v6
	v_lshlrev_b32_e32 v5, 5, v8
	v_ashrrev_i16_sdwa v1, v2, sext(v1) dst_sel:DWORD dst_unused:UNUSED_PAD src0_sel:DWORD src1_sel:BYTE_0
	s_movk_i32 s2, 0x1040
	v_and_b32_e32 v11, 32, v5
	v_bfe_i32 v12, v1, 0, 16
	v_mul_lo_u32 v4, v4, s2
	v_add_u32_e32 v1, v11, v12
	v_mul_lo_u32 v3, v3, s2
	v_add_lshl_u32 v128, v4, v1, 1
	v_add_lshl_u32 v130, v1, v3, 1
	v_ashrrev_i32_e32 v1, 31, v0
	v_lshrrev_b32_e32 v1, 22, v1
	v_add_u32_e32 v1, v0, v1
	v_ashrrev_i32_e32 v13, 10, v1
	v_mul_i32_i24_e32 v1, 0x400, v13
	v_sub_u32_e32 v0, v0, v1
	v_lshrrev_b32_e32 v1, 4, v0
	v_bitop3_b32 v0, v1, v0, 32 bitop3:0x6c
	v_ashrrev_i32_e32 v1, 31, v0
	v_lshrrev_b32_e32 v1, 26, v1
	v_add_u32_e32 v1, v0, v1
	v_lshlrev_b32_e32 v3, 3, v13
	v_ashrrev_i32_e32 v14, 6, v1
	v_and_b32_e32 v3, -16, v3
	v_add_u32_e32 v3, v14, v3
	v_and_b32_e32 v4, 3, v14
	s_ashr_i32 s19, s8, 31
	v_and_or_b32 v4, v3, s4, v4
	s_lshr_b32 s4, s19, 29
	s_add_i32 s4, s8, s4
	s_ashr_i32 s5, s4, 3
	s_and_b32 s4, s4, -8
	s_lshr_b32 s3, s95, 8
	s_sub_i32 s4, s8, s4
	s_cmp_lt_i32 s4, 0
	s_movk_i32 s22, 0x159
	s_cselect_b32 s20, s22, 0x158
	s_mul_i32 s4, s4, s20
	s_add_i32 s4, s4, s5
	s_mul_hi_i32 s5, s4, 0x2fa0be83
	s_lshr_b32 s20, s5, 31
	s_ashr_i32 s5, s5, 7
	s_add_i32 s5, s5, s20
	s_lshl_b32 s20, s5, 3
	s_mulk_i32 s5, 0x2b0
	s_sub_i32 s5, s4, s5
	s_sext_i32_i16 s4, s5
	s_bfe_u32 s4, s4, 0x3001c
	s_add_i32 s21, s5, s4
	s_sext_i32_i16 s23, s21
	s_and_b32 s21, s21, 0xfff8
	v_lshrrev_b32_e32 v5, 2, v3
	v_lshlrev_b32_e32 v6, 1, v3
	v_and_b32_e32 v1, 0xc0, v1
	s_sub_i32 s5, s5, s21
	v_and_b32_e32 v5, 4, v5
	v_and_b32_e32 v6, 24, v6
	v_sub_u32_e32 v0, v0, v1
	s_lshr_b32 s4, s23, 3
	s_sext_i32_i16 s5, s5
	s_ashr_i32 s23, s23, 3
	v_or3_b32 v4, v4, v5, v6
	v_lshlrev_b32_e32 v5, 5, v13
	v_ashrrev_i16_sdwa v0, v2, sext(v0) dst_sel:DWORD dst_unused:UNUSED_PAD src0_sel:DWORD src1_sel:BYTE_0
	s_add_i32 s20, s20, s5
	s_mul_hi_i32 s24, s23, 0x208000
	s_mul_i32 s23, s23, 0x208000
	v_and_b32_e32 v15, 32, v5
	v_bfe_i32 v16, v0, 0, 16
	s_add_u32 s50, s36, s23
	v_mul_lo_u32 v4, v4, s2
	v_add_u32_e32 v0, v15, v16
	s_addc_u32 s51, s37, s24
	s_add_i32 s23, s17, 0
	v_add_lshl_u32 v132, v4, v0, 1
	s_add_i32 m0, s23, 0x10000
	s_mul_i32 s21, s20, 0x208000
	global_load_lds_dwordx4 v132, s[50:51]
	s_add_i32 m0, s23, 0x12000
	s_add_u32 s24, s50, 0x104000
	global_load_lds_dwordx4 v128, s[50:51]
	s_addc_u32 s25, s51, 0
	s_add_i32 m0, s23, 0x14000
	s_mul_hi_i32 s5, s20, 0x208000
	global_load_lds_dwordx4 v132, s[24:25]
	s_add_i32 m0, s23, 0x16000
	s_add_u32 s48, s26, s21
	v_mul_lo_u32 v1, v3, s2
	global_load_lds_dwordx4 v128, s[24:25]
	s_addc_u32 s49, s27, s5
	s_add_i32 s24, s23, 0x2000
	v_add_lshl_u32 v134, v0, v1, 1
	s_mov_b32 m0, s23
	s_add_u32 s38, s48, 0x104000
	global_load_lds_dwordx4 v134, s[48:49]
	s_mov_b32 m0, s24
	s_addc_u32 s39, s49, 0
	s_add_i32 s25, s23, 0x4000
	global_load_lds_dwordx4 v130, s[48:49]
	s_mov_b32 m0, s25
	s_add_i32 s29, s23, 0x6000
	global_load_lds_dwordx4 v134, s[38:39]
	s_mov_b32 m0, s29
	v_mov_b32_e32 v133, 0
	global_load_lds_dwordx4 v130, s[38:39]
	v_mov_b32_e32 v129, v133
	v_mov_b32_e32 v135, v133
	v_mov_b32_e32 v131, v133
	s_cmp_eq_u32 s3, 1
	s_mov_b32 s54, 0
	v_lshl_add_u64 v[6:7], s[50:51], 0, v[132:133]
	v_lshl_add_u64 v[4:5], s[50:51], 0, v[128:129]
	v_lshl_add_u64 v[0:1], s[48:49], 0, v[134:135]
	s_cselect_b64 s[38:39], -1, 0
	s_cmp_lg_u32 s3, 1
	v_lshl_add_u64 v[2:3], s[48:49], 0, v[130:131]
	s_cbranch_scc1 .LBB0_223
	s_barrier

; __global__ void __launch_bounds__(NWAVES * 64, 2) fwd(Args args) {
;     ...
;           for (;;) {
;             __syncthreads();
;             if (tid == 0) MISC[16] = qpre;
;             __syncthreads();
;             constexpr int NB64 = (NCB * 3) / 4, NB16 = (NCB - NB64) * 4;
;             const unsigned q = MISC[16]; if (q >= 512u + (DEFER_AT == 5 ? (unsigned)(NB64 + NB16) : 0u)) break;
.LBB0_643:
	s_or_b64 exec, exec, s[2:3]
	s_waitcnt lgkmcnt(0)
	s_barrier
	ds_read_b32 v0, v164
	s_movk_i32 s2, 0x54e
	s_waitcnt lgkmcnt(0)
	v_cmp_lt_u32_e64 s[2:3], s2, v0
	v_readfirstlane_b32 s25, v0
	s_and_b64 vcc, exec, s[2:3]
	s_cbranch_vccnz .LBB0_640
	s_and_saveexec_b64 s[6:7], s[4:5]
	s_cbranch_execz .LBB0_646
	v_mov_b32_e32 v0, v161
	s_nop 0
	v_ashrrev_i32_e32 v1, 31, v0
	v_lshl_add_u64 v[0:1], v[0:1], 2, s[44:45]
	global_atomic_add v162, v[0:1], v165, off sc0

; __global__ void __launch_bounds__(NWAVES * 64, 2) fwd(Args args) {
;     ...
;             if (!conv) attn_wg(PROJ, CONCAT, idx, L, tid, lane, wave);
;             else {
;                 const bool small = idx >= NB64; const int first = NI0 + (small ? NB64 * 64 + (idx - NB64) * 16 : idx * 64) + wave;
;                 f32x4 va[16], vb[16]; P0T_DECL(a); P0T_DECL(b);
.LBB0_679:
	s_and_b64 vcc, exec, s[4:5]
	s_cbranch_vccz .LBB0_640
	s_add_i32 s4, s25, 0xfffffe00
	s_lshl_b32 s58, s4, 4
	s_addk_i32 s58, 0x3210
	s_lshl_b32 s42, s4, 6
	s_cmpk_gt_u32 s4, 0x10a
	s_cselect_b32 s5, s58, s42
	s_add_i32 s25, s86, s5
	s_cmpk_lt_u32 s4, 0x10b
	s_mov_b64 s[4:5], -1
	s_cbranch_scc0 .LBB0_882
	s_add_i32 s42, s42, s28
	s_cmpk_gt_u32 s42, 0xfff
	s_cbranch_scc0 .LBB0_685
	s_cmpk_gt_u32 s42, 0x65ff
	s_cbranch_scc0 .LBB0_942
	s_and_b32 s4, s42, 0x7ffffc0
	s_add_i32 s64, s4, 0xffff9a00
	s_mov_b64 s[70:71], 0
	s_cbranch_execz .LBB0_943

; #define LAS __attribute__((address_space(3)))
; __device__ __forceinline__ unsigned pk2(float lo, float hi) { return pg8::cvt_pk_bf16(lo, hi); }
; #define REFRESH_IDS() do { lane = fresh_lane(); tid = wave * 64 + lane; } while (0)
; __device__ __forceinline__ void p0_load(const float* W, int N, int k0, int n0, int lane, f32x4 (&v)[16]) {
;     const int c = lane & 15, rq = lane >> 4;
;     int col = n0 + 4 * c; col = col < N - 4 ? col : N - 4;
;     const float* p = W + (size_t)(k0 + rq) * N + col;
; #pragma unroll
;     for (int j = 0; j < 16; ++j) v[j] = __builtin_nontemporal_load((const f32x4*)(p + (size_t)(4 * j) * N));
; }
; __device__ __forceinline__ void p0_finish(bf16* WT, const float* gain, int N, int k0, int n0, int ldw, int blk, int off, int lane, const f32x4 (&v)[16], LAS float* scr) {
;     const int c = lane & 15, rq = lane >> 4, c8 = lane & 7;
;     f32x4 g0 = {1.f, 1.f, 1.f, 1.f}, g1 = g0;
;     if (gain) { g0 = *(const f32x4*)(gain + k0 + 8 * c8); g1 = *(const f32x4*)(gain + k0 + 8 * c8 + 4); }
; #pragma unroll
;     for (int j = 0; j < 16; ++j) { LAS float* s = scr + (4 * j + rq) * 65 + 4 * c; s[0] = v[j][0]; s[1] = v[j][1]; s[2] = v[j][2]; s[3] = v[j][3]; }
;     asm volatile("s_waitcnt lgkmcnt(0)" ::: "memory");
; #pragma unroll
;     for (int jj = 0; jj < 8; ++jj) { const int n = (lane >> 3) + 8 * jj; const LAS float* s = scr + (8 * c8) * 65 + n;
;         u32x4 o; o.x = pk2(s[0 * 65] * g0[0], s[1 * 65] * g0[1]); o.y = pk2(s[2 * 65] * g0[2], s[3 * 65] * g0[3]); o.z = pk2(s[4 * 65] * g1[0], s[5 * 65] * g1[1]); o.w = pk2(s[6 * 65] * g1[2], s[7 * 65] * g1[3]);
;         const int ng = n0 + n;
;         if (ng < N) { const int row = (ng >> 7) * blk + (ng & 127) + off; __builtin_nontemporal_store(o, (u32x4*)(WT + (size_t)row * ldw + k0 + 8 * c8)); } }
; __global__ void __launch_bounds__(NWAVES * 64, 2) fwd(Args args) {
;     ...
;     if (IN(8)) {
;         REFRESH_IDS();
.LBB0_1119:
	s_cmp_lt_i32 s96, 9
	s_cselect_b64 s[2:3], -1, 0
	s_cmp_gt_i32 s97, 8
	s_cselect_b64 s[4:5], -1, 0
	s_and_b64 s[2:3], s[2:3], s[4:5]
	s_andn2_b64 vcc, exec, s[2:3]
	s_cbranch_vccnz .LBB0_1196
	s_cmpk_lt_u32 s8, 0xc0
	s_cbranch_scc1 .Lhn_done
	v_writelane_b32 v238, s0, 0
	v_writelane_b32 v238, s1, 1
	v_writelane_b32 v238, s2, 2
	v_writelane_b32 v238, s3, 3
	v_writelane_b32 v238, s4, 4
	v_writelane_b32 v238, s5, 5
	v_writelane_b32 v238, s6, 6
	v_writelane_b32 v238, s7, 7
	v_writelane_b32 v238, s8, 8
	v_writelane_b32 v238, s9, 9
	v_writelane_b32 v238, s10, 10
	v_writelane_b32 v238, s11, 11
	v_writelane_b32 v238, s12, 12
	v_writelane_b32 v238, s13, 13
	v_writelane_b32 v238, s14, 14
	v_writelane_b32 v238, s15, 15
	v_writelane_b32 v238, s16, 16
	v_writelane_b32 v238, s17, 17
	v_writelane_b32 v238, s18, 18
	v_writelane_b32 v238, s19, 19
	v_writelane_b32 v238, s20, 20
	v_writelane_b32 v238, s21, 21
	v_writelane_b32 v238, s22, 22
	v_writelane_b32 v238, s23, 23
	v_writelane_b32 v238, s24, 24
	v_writelane_b32 v238, s25, 25
	v_writelane_b32 v238, s26, 26
	v_writelane_b32 v238, s27, 27
	v_writelane_b32 v238, s28, 28
	v_writelane_b32 v238, s29, 29
	v_writelane_b32 v238, s30, 30
	v_writelane_b32 v238, s31, 31
	v_writelane_b32 v238, s32, 32
	v_writelane_b32 v238, s33, 33
	v_writelane_b32 v238, s34, 34
	v_writelane_b32 v238, s35, 35
	v_writelane_b32 v238, s36, 36
	v_writelane_b32 v238, s37, 37
	v_writelane_b32 v238, s38, 38
	v_writelane_b32 v238, s39, 39
	v_writelane_b32 v238, s40, 40
	v_writelane_b32 v238, s41, 41
	v_writelane_b32 v238, s42, 42
	v_writelane_b32 v238, s43, 43
	v_writelane_b32 v238, s44, 44
	v_writelane_b32 v238, s45, 45
	v_writelane_b32 v238, s46, 46
	v_writelane_b32 v238, s47, 47
	v_writelane_b32 v238, s48, 48
	v_writelane_b32 v238, s49, 49
	v_writelane_b32 v238, s50, 50
	v_writelane_b32 v238, s51, 51
	v_writelane_b32 v238, s52, 52
	v_writelane_b32 v238, s53, 53
	v_writelane_b32 v238, s54, 54
	v_writelane_b32 v238, s55, 55
	v_writelane_b32 v238, s56, 56
	v_writelane_b32 v238, s57, 57
	v_writelane_b32 v238, s58, 58
	v_writelane_b32 v238, s59, 59
	v_writelane_b32 v238, s60, 60
	v_writelane_b32 v238, s61, 61
	v_writelane_b32 v238, s62, 62
	v_writelane_b32 v238, s63, 63
	v_writelane_b32 v239, s64, 0
	v_writelane_b32 v239, s65, 1
	v_writelane_b32 v239, s66, 2
	v_writelane_b32 v239, s67, 3
	v_writelane_b32 v239, s68, 4
	v_writelane_b32 v239, s69, 5
	v_writelane_b32 v239, s70, 6
	v_writelane_b32 v239, s71, 7
	v_writelane_b32 v239, s72, 8
	v_writelane_b32 v239, s73, 9
	v_writelane_b32 v239, s74, 10
	v_writelane_b32 v239, s75, 11
	v_writelane_b32 v239, s76, 12
	v_writelane_b32 v239, s77, 13
	v_writelane_b32 v239, s78, 14
	v_writelane_b32 v239, s79, 15
	v_writelane_b32 v239, s80, 16
	v_writelane_b32 v239, s81, 17
	v_writelane_b32 v239, s82, 18
	v_writelane_b32 v239, s83, 19
	v_writelane_b32 v239, s84, 20
	v_writelane_b32 v239, s85, 21
	v_writelane_b32 v239, s86, 22
	v_writelane_b32 v239, s87, 23
	v_writelane_b32 v239, s88, 24
	v_writelane_b32 v239, s89, 25
	v_writelane_b32 v239, s90, 26
	v_writelane_b32 v239, s91, 27
	v_writelane_b32 v239, s92, 28
	v_writelane_b32 v239, s93, 29
	v_writelane_b32 v239, s94, 30
	v_writelane_b32 v239, s95, 31
	v_writelane_b32 v239, s96, 32
	v_writelane_b32 v239, s97, 33
	v_writelane_b32 v239, s98, 34
	v_writelane_b32 v239, s99, 35
	v_writelane_b32 v239, s100, 36
	v_writelane_b32 v239, s101, 37
	v_writelane_b32 v239, vcc_lo, 38
	v_writelane_b32 v239, vcc_hi, 39
	v_writelane_b32 v239, m0, 40
	s_add_i32 s16, s8, 0xffffff40
	s_lshl_b32 s16, s16, 3
	s_add_i32 s16, s16, s28
	s_load_dwordx2 s[30:31], s[0:1], 0x78
	v_mbcnt_lo_u32_b32 v146, -1, 0
	v_mbcnt_hi_u32_b32 v146, -1, v146
	s_and_b32 s17, s16, 63
	s_lshr_b32 s18, s16, 6
	s_add_i32 s18, s18, 4
	s_mul_i32 s19, s28, 0x4100
	v_lshrrev_b32_e32 v131, 4, v146
	v_and_b32_e32 v133, 15, v146
	v_mul_u32_u24_e32 v128, 0x104, v131
	v_lshl_add_u32 v128, v133, 4, v128
	v_add_u32_e32 v128, s19, v128
	v_lshlrev_b32_e32 v131, 14, v131
	v_lshl_add_u32 v131, v133, 4, v131
	v_and_b32_e32 v133, 7, v146
	v_lshrrev_b32_e32 v132, 3, v146
	v_mul_u32_u24_e32 v129, 0x820, v133
	v_lshl_add_u32 v129, v132, 2, v129
	v_add_u32_e32 v129, s19, v129
	v_add_u32_e32 v130, 0x400, v129
	v_mul_u32_u24_e32 v132, 0x5680, v132
	v_lshl_add_u32 v132, v133, 4, v132
	s_waitcnt lgkmcnt(0)
; __device__ __forceinline__ void p0_load(const float* W, int N, int k0, int n0, int lane, f32x4 (&v)[16]) {
;     const int c = lane & 15, rq = lane >> 4;
;     int col = n0 + 4 * c; col = col < N - 4 ? col : N - 4;
;     const float* p = W + (size_t)(k0 + rq) * N + col;
; #pragma unroll
;     for (int j = 0; j < 16; ++j) v[j] = __builtin_nontemporal_load((const f32x4*)(p + (size_t)(4 * j) * N));
; }
	s_lshl_b32 s2, s17, 8
	s_add_u32 s20, s30, s2
	s_addc_u32 s21, s31, 0
	s_lshr_b32 s3, s18, 12
	s_lshl_b32 s2, s18, 20
	s_add_u32 s20, s20, s2
	s_addc_u32 s21, s21, s3
	s_add_u32 s22, s14, 0x25000000
	s_addc_u32 s23, s15, 0
	s_mul_i32 s2, s17, 0x15a000
	s_add_u32 s22, s22, s2
	s_addc_u32 s23, s23, 0
	s_lshl_b32 s2, s18, 7
	s_add_u32 s22, s22, s2
	s_addc_u32 s23, s23, 0
	s_mov_b32 s26, 0
	s_mov_b32 s27, 1
	global_load_dwordx4 v[0:3], v131, s[20:21] nt
	s_add_u32 s24, s20, 0x10000
	s_addc_u32 s25, s21, 0
	global_load_dwordx4 v[4:7], v131, s[24:25] nt
	s_add_u32 s24, s20, 0x20000
	s_addc_u32 s25, s21, 0
	global_load_dwordx4 v[8:11], v131, s[24:25] nt
	s_add_u32 s24, s20, 0x30000
	s_addc_u32 s25, s21, 0
	global_load_dwordx4 v[12:15], v131, s[24:25] nt
	s_add_u32 s24, s20, 0x40000
	s_addc_u32 s25, s21, 0
	global_load_dwordx4 v[16:19], v131, s[24:25] nt
	s_add_u32 s24, s20, 0x50000
	s_addc_u32 s25, s21, 0
	global_load_dwordx4 v[20:23], v131, s[24:25] nt
	s_add_u32 s24, s20, 0x60000
	s_addc_u32 s25, s21, 0
	global_load_dwordx4 v[24:27], v131, s[24:25] nt
	s_add_u32 s24, s20, 0x70000
	s_addc_u32 s25, s21, 0
	global_load_dwordx4 v[28:31], v131, s[24:25] nt
	s_add_u32 s24, s20, 0x80000
	s_addc_u32 s25, s21, 0
	global_load_dwordx4 v[32:35], v131, s[24:25] nt
	s_add_u32 s24, s20, 0x90000
	s_addc_u32 s25, s21, 0
	global_load_dwordx4 v[36:39], v131, s[24:25] nt
	s_add_u32 s24, s20, 0xa0000
	s_addc_u32 s25, s21, 0
	global_load_dwordx4 v[40:43], v131, s[24:25] nt
	s_add_u32 s24, s20, 0xb0000
	s_addc_u32 s25, s21, 0
	global_load_dwordx4 v[44:47], v131, s[24:25] nt
	s_add_u32 s24, s20, 0xc0000
	s_addc_u32 s25, s21, 0
	global_load_dwordx4 v[48:51], v131, s[24:25] nt
	s_add_u32 s24, s20, 0xd0000
	s_addc_u32 s25, s21, 0
	global_load_dwordx4 v[52:55], v131, s[24:25] nt
	s_add_u32 s24, s20, 0xe0000
	s_addc_u32 s25, s21, 0
	global_load_dwordx4 v[56:59], v131, s[24:25] nt
	s_add_u32 s24, s20, 0xf0000
	s_addc_u32 s25, s21, 0
	global_load_dwordx4 v[60:63], v131, s[24:25] nt
	s_cmp_lt_u32 s27, 21
	s_cselect_b32 s2, 0x800000, 0
	s_add_u32 s20, s20, s2
	s_addc_u32 s21, s21, 0
	s_add_i32 s27, s27, 1
	global_load_dwordx4 v[64:67], v131, s[20:21] nt
	s_add_u32 s24, s20, 0x10000
	s_addc_u32 s25, s21, 0
	global_load_dwordx4 v[68:71], v131, s[24:25] nt
	s_add_u32 s24, s20, 0x20000
	s_addc_u32 s25, s21, 0
	global_load_dwordx4 v[72:75], v131, s[24:25] nt
	s_add_u32 s24, s20, 0x30000
	s_addc_u32 s25, s21, 0
	global_load_dwordx4 v[76:79], v131, s[24:25] nt
	s_add_u32 s24, s20, 0x40000
	s_addc_u32 s25, s21, 0
	global_load_dwordx4 v[80:83], v131, s[24:25] nt
	s_add_u32 s24, s20, 0x50000
	s_addc_u32 s25, s21, 0
	global_load_dwordx4 v[84:87], v131, s[24:25] nt
	s_add_u32 s24, s20, 0x60000
	s_addc_u32 s25, s21, 0
	global_load_dwordx4 v[88:91], v131, s[24:25] nt
	s_add_u32 s24, s20, 0x70000
	s_addc_u32 s25, s21, 0
	global_load_dwordx4 v[92:95], v131, s[24:25] nt
	s_add_u32 s24, s20, 0x80000
	s_addc_u32 s25, s21, 0
	global_load_dwordx4 v[96:99], v131, s[24:25] nt
	s_add_u32 s24, s20, 0x90000
	s_addc_u32 s25, s21, 0
	global_load_dwordx4 v[100:103], v131, s[24:25] nt
	s_add_u32 s24, s20, 0xa0000
	s_addc_u32 s25, s21, 0
	global_load_dwordx4 v[104:107], v131, s[24:25] nt
	s_add_u32 s24, s20, 0xb0000
	s_addc_u32 s25, s21, 0
	global_load_dwordx4 v[108:111], v131, s[24:25] nt
	s_add_u32 s24, s20, 0xc0000
	s_addc_u32 s25, s21, 0
	global_load_dwordx4 v[112:115], v131, s[24:25] nt
	s_add_u32 s24, s20, 0xd0000
	s_addc_u32 s25, s21, 0
	global_load_dwordx4 v[116:119], v131, s[24:25] nt
	s_add_u32 s24, s20, 0xe0000
	s_addc_u32 s25, s21, 0
	global_load_dwordx4 v[120:123], v131, s[24:25] nt
	s_add_u32 s24, s20, 0xf0000
	s_addc_u32 s25, s21, 0
	global_load_dwordx4 v[124:127], v131, s[24:25] nt

; #define LAS __attribute__((address_space(3)))
; __device__ __forceinline__ unsigned pk2(float lo, float hi) { return pg8::cvt_pk_bf16(lo, hi); }
; __device__ __forceinline__ void p0_load(const float* W, int N, int k0, int n0, int lane, f32x4 (&v)[16]) {
;     const int c = lane & 15, rq = lane >> 4;
;     int col = n0 + 4 * c; col = col < N - 4 ? col : N - 4;
;     const float* p = W + (size_t)(k0 + rq) * N + col;
; #pragma unroll
;     for (int j = 0; j < 16; ++j) v[j] = __builtin_nontemporal_load((const f32x4*)(p + (size_t)(4 * j) * N));
; }
; __device__ __forceinline__ void p0_finish(bf16* WT, const float* gain, int N, int k0, int n0, int ldw, int blk, int off, int lane, const f32x4 (&v)[16], LAS float* scr) {
;     const int c = lane & 15, rq = lane >> 4, c8 = lane & 7;
;     f32x4 g0 = {1.f, 1.f, 1.f, 1.f}, g1 = g0;
;     if (gain) { g0 = *(const f32x4*)(gain + k0 + 8 * c8); g1 = *(const f32x4*)(gain + k0 + 8 * c8 + 4); }
; #pragma unroll
;     for (int j = 0; j < 16; ++j) { LAS float* s = scr + (4 * j + rq) * 65 + 4 * c; s[0] = v[j][0]; s[1] = v[j][1]; s[2] = v[j][2]; s[3] = v[j][3]; }
;     asm volatile("s_waitcnt lgkmcnt(0)" ::: "memory");
; #pragma unroll
;     for (int jj = 0; jj < 8; ++jj) { const int n = (lane >> 3) + 8 * jj; const LAS float* s = scr + (8 * c8) * 65 + n;
;         u32x4 o; o.x = pk2(s[0 * 65] * g0[0], s[1 * 65] * g0[1]); o.y = pk2(s[2 * 65] * g0[2], s[3 * 65] * g0[3]); o.z = pk2(s[4 * 65] * g1[0], s[5 * 65] * g1[1]); o.w = pk2(s[6 * 65] * g1[2], s[7 * 65] * g1[3]);
;         const int ng = n0 + n;
;         if (ng < N) { const int row = (ng >> 7) * blk + (ng & 127) + off; __builtin_nontemporal_store(o, (u32x4*)(WT + (size_t)row * ldw + k0 + 8 * c8)); } }
;     asm volatile("s_waitcnt lgkmcnt(0)" ::: "memory");
; }
.Lhn_w0:
	s_waitcnt vmcnt(32)
	ds_write2_b32 v128, v0, v1 offset1:1
	ds_write2_b32 v128, v2, v3 offset0:2 offset1:3
	v_add_u32_e32 v133, 0x410, v128
	ds_write2_b32 v133, v4, v5 offset1:1
	ds_write2_b32 v133, v6, v7 offset0:2 offset1:3
	v_add_u32_e32 v147, 0x820, v128
	ds_write2_b32 v147, v8, v9 offset1:1
	ds_write2_b32 v147, v10, v11 offset0:2 offset1:3
	v_add_u32_e32 v133, 0xc30, v128
	ds_write2_b32 v133, v12, v13 offset1:1
	ds_write2_b32 v133, v14, v15 offset0:2 offset1:3
	v_add_u32_e32 v147, 0x1040, v128
	ds_write2_b32 v147, v16, v17 offset1:1
	ds_write2_b32 v147, v18, v19 offset0:2 offset1:3
	v_add_u32_e32 v133, 0x1450, v128
	ds_write2_b32 v133, v20, v21 offset1:1
	ds_write2_b32 v133, v22, v23 offset0:2 offset1:3
	v_add_u32_e32 v147, 0x1860, v128
	ds_write2_b32 v147, v24, v25 offset1:1
	ds_write2_b32 v147, v26, v27 offset0:2 offset1:3
	v_add_u32_e32 v133, 0x1c70, v128
	ds_write2_b32 v133, v28, v29 offset1:1
	ds_write2_b32 v133, v30, v31 offset0:2 offset1:3
	v_add_u32_e32 v147, 0x2080, v128
	ds_write2_b32 v147, v32, v33 offset1:1
	ds_write2_b32 v147, v34, v35 offset0:2 offset1:3
	v_add_u32_e32 v133, 0x2490, v128
	ds_write2_b32 v133, v36, v37 offset1:1
	ds_write2_b32 v133, v38, v39 offset0:2 offset1:3
	v_add_u32_e32 v147, 0x28a0, v128
	ds_write2_b32 v147, v40, v41 offset1:1
	ds_write2_b32 v147, v42, v43 offset0:2 offset1:3
	v_add_u32_e32 v133, 0x2cb0, v128
	ds_write2_b32 v133, v44, v45 offset1:1
	ds_write2_b32 v133, v46, v47 offset0:2 offset1:3
	v_add_u32_e32 v147, 0x30c0, v128
	ds_write2_b32 v147, v48, v49 offset1:1
	ds_write2_b32 v147, v50, v51 offset0:2 offset1:3
	v_add_u32_e32 v133, 0x34d0, v128
	ds_write2_b32 v133, v52, v53 offset1:1
	ds_write2_b32 v133, v54, v55 offset0:2 offset1:3
	v_add_u32_e32 v147, 0x38e0, v128
	ds_write2_b32 v147, v56, v57 offset1:1
	ds_write2_b32 v147, v58, v59 offset0:2 offset1:3
	v_add_u32_e32 v133, 0x3cf0, v128
	ds_write2_b32 v133, v60, v61 offset1:1
	ds_write2_b32 v133, v62, v63 offset0:2 offset1:3
	s_waitcnt lgkmcnt(0)
	s_cmp_lt_u32 s27, 21
	s_cselect_b32 s2, 0x800000, 0
	s_add_u32 s20, s20, s2
	s_addc_u32 s21, s21, 0
	s_add_i32 s27, s27, 1
	global_load_dwordx4 v[0:3], v131, s[20:21] nt
	s_add_u32 s24, s20, 0x10000
	s_addc_u32 s25, s21, 0
	global_load_dwordx4 v[4:7], v131, s[24:25] nt
	s_add_u32 s24, s20, 0x20000
	s_addc_u32 s25, s21, 0
	global_load_dwordx4 v[8:11], v131, s[24:25] nt
	s_add_u32 s24, s20, 0x30000
	s_addc_u32 s25, s21, 0
	global_load_dwordx4 v[12:15], v131, s[24:25] nt
	s_add_u32 s24, s20, 0x40000
	s_addc_u32 s25, s21, 0
	global_load_dwordx4 v[16:19], v131, s[24:25] nt
	s_add_u32 s24, s20, 0x50000
	s_addc_u32 s25, s21, 0
	global_load_dwordx4 v[20:23], v131, s[24:25] nt
	s_add_u32 s24, s20, 0x60000
	s_addc_u32 s25, s21, 0
	global_load_dwordx4 v[24:27], v131, s[24:25] nt
	s_add_u32 s24, s20, 0x70000
	s_addc_u32 s25, s21, 0
	global_load_dwordx4 v[28:31], v131, s[24:25] nt
	s_add_u32 s24, s20, 0x80000
	s_addc_u32 s25, s21, 0
	global_load_dwordx4 v[32:35], v131, s[24:25] nt
	s_add_u32 s24, s20, 0x90000
	s_addc_u32 s25, s21, 0
	global_load_dwordx4 v[36:39], v131, s[24:25] nt
	s_add_u32 s24, s20, 0xa0000
	s_addc_u32 s25, s21, 0
	global_load_dwordx4 v[40:43], v131, s[24:25] nt
	s_add_u32 s24, s20, 0xb0000
	s_addc_u32 s25, s21, 0
	global_load_dwordx4 v[44:47], v131, s[24:25] nt
	s_add_u32 s24, s20, 0xc0000
	s_addc_u32 s25, s21, 0
	global_load_dwordx4 v[48:51], v131, s[24:25] nt
	s_add_u32 s24, s20, 0xd0000
	s_addc_u32 s25, s21, 0
	global_load_dwordx4 v[52:55], v131, s[24:25] nt
	s_add_u32 s24, s20, 0xe0000
	s_addc_u32 s25, s21, 0
	global_load_dwordx4 v[56:59], v131, s[24:25] nt
	s_add_u32 s24, s20, 0xf0000
	s_addc_u32 s25, s21, 0
	global_load_dwordx4 v[60:63], v131, s[24:25] nt
	ds_read2_b32 v[134:135], v129 offset0:0 offset1:65
	ds_read2_b32 v[136:137], v129 offset0:130 offset1:195
	ds_read2_b32 v[138:139], v130 offset0:4 offset1:69
	ds_read2_b32 v[140:141], v130 offset0:134 offset1:199
	ds_read2_b32 v[148:149], v129 offset0:8 offset1:73
	ds_read2_b32 v[150:151], v129 offset0:138 offset1:203
	ds_read2_b32 v[152:153], v130 offset0:12 offset1:77
	ds_read2_b32 v[154:155], v130 offset0:142 offset1:207
	s_mov_b64 s[24:25], s[22:23]
	s_waitcnt lgkmcnt(4)
	v_cvt_pk_bf16_f32 v142, v134, v135
	v_cvt_pk_bf16_f32 v143, v136, v137
	v_cvt_pk_bf16_f32 v144, v138, v139
	v_cvt_pk_bf16_f32 v145, v140, v141
	global_store_dwordx4 v132, v[142:145], s[24:25] nt
	ds_read2_b32 v[134:135], v129 offset0:16 offset1:81
	ds_read2_b32 v[136:137], v129 offset0:146 offset1:211
	ds_read2_b32 v[138:139], v130 offset0:20 offset1:85
	ds_read2_b32 v[140:141], v130 offset0:150 offset1:215
	s_add_u32 s24, s22, 0x2b400
	s_addc_u32 s25, s23, 0
	s_waitcnt lgkmcnt(4)
	v_cvt_pk_bf16_f32 v156, v148, v149
	v_cvt_pk_bf16_f32 v157, v150, v151
	v_cvt_pk_bf16_f32 v158, v152, v153
	v_cvt_pk_bf16_f32 v159, v154, v155
	global_store_dwordx4 v132, v[156:159], s[24:25] nt
	ds_read2_b32 v[148:149], v129 offset0:24 offset1:89
	ds_read2_b32 v[150:151], v129 offset0:154 offset1:219
	ds_read2_b32 v[152:153], v130 offset0:28 offset1:93
	ds_read2_b32 v[154:155], v130 offset0:158 offset1:223
	s_add_u32 s24, s22, 0x56800
	s_addc_u32 s25, s23, 0
	s_waitcnt lgkmcnt(4)
	v_cvt_pk_bf16_f32 v142, v134, v135
	v_cvt_pk_bf16_f32 v143, v136, v137
	v_cvt_pk_bf16_f32 v144, v138, v139
	v_cvt_pk_bf16_f32 v145, v140, v141
	global_store_dwordx4 v132, v[142:145], s[24:25] nt
	ds_read2_b32 v[134:135], v129 offset0:32 offset1:97
	ds_read2_b32 v[136:137], v129 offset0:162 offset1:227
	ds_read2_b32 v[138:139], v130 offset0:36 offset1:101
	ds_read2_b32 v[140:141], v130 offset0:166 offset1:231
	s_add_u32 s24, s22, 0x81c00
	s_addc_u32 s25, s23, 0
	s_waitcnt lgkmcnt(4)
; #define LAS __attribute__((address_space(3)))
; __device__ __forceinline__ unsigned pk2(float lo, float hi) { return pg8::cvt_pk_bf16(lo, hi); }
; __device__ __forceinline__ void p0_finish(bf16* WT, const float* gain, int N, int k0, int n0, int ldw, int blk, int off, int lane, const f32x4 (&v)[16], LAS float* scr) {
;     const int c = lane & 15, rq = lane >> 4, c8 = lane & 7;
;     f32x4 g0 = {1.f, 1.f, 1.f, 1.f}, g1 = g0;
;     if (gain) { g0 = *(const f32x4*)(gain + k0 + 8 * c8); g1 = *(const f32x4*)(gain + k0 + 8 * c8 + 4); }
; #pragma unroll
;     for (int j = 0; j < 16; ++j) { LAS float* s = scr + (4 * j + rq) * 65 + 4 * c; s[0] = v[j][0]; s[1] = v[j][1]; s[2] = v[j][2]; s[3] = v[j][3]; }
;     asm volatile("s_waitcnt lgkmcnt(0)" ::: "memory");
; #pragma unroll
;     for (int jj = 0; jj < 8; ++jj) { const int n = (lane >> 3) + 8 * jj; const LAS float* s = scr + (8 * c8) * 65 + n;
;         u32x4 o; o.x = pk2(s[0 * 65] * g0[0], s[1 * 65] * g0[1]); o.y = pk2(s[2 * 65] * g0[2], s[3 * 65] * g0[3]); o.z = pk2(s[4 * 65] * g1[0], s[5 * 65] * g1[1]); o.w = pk2(s[6 * 65] * g1[2], s[7 * 65] * g1[3]);
;         const int ng = n0 + n;
;         if (ng < N) { const int row = (ng >> 7) * blk + (ng & 127) + off; __builtin_nontemporal_store(o, (u32x4*)(WT + (size_t)row * ldw + k0 + 8 * c8)); } }
;     asm volatile("s_waitcnt lgkmcnt(0)" ::: "memory");
; }
	v_cvt_pk_bf16_f32 v156, v148, v149
	v_cvt_pk_bf16_f32 v157, v150, v151
	v_cvt_pk_bf16_f32 v158, v152, v153
	v_cvt_pk_bf16_f32 v159, v154, v155
	global_store_dwordx4 v132, v[156:159], s[24:25] nt
	ds_read2_b32 v[148:149], v129 offset0:40 offset1:105
	ds_read2_b32 v[150:151], v129 offset0:170 offset1:235
	ds_read2_b32 v[152:153], v130 offset0:44 offset1:109
	ds_read2_b32 v[154:155], v130 offset0:174 offset1:239
	s_add_u32 s24, s22, 0xad000
	s_addc_u32 s25, s23, 0
	s_waitcnt lgkmcnt(4)
	v_cvt_pk_bf16_f32 v142, v134, v135
	v_cvt_pk_bf16_f32 v143, v136, v137
	v_cvt_pk_bf16_f32 v144, v138, v139
	v_cvt_pk_bf16_f32 v145, v140, v141
	global_store_dwordx4 v132, v[142:145], s[24:25] nt
	ds_read2_b32 v[134:135], v129 offset0:48 offset1:113
	ds_read2_b32 v[136:137], v129 offset0:178 offset1:243
	ds_read2_b32 v[138:139], v130 offset0:52 offset1:117
	ds_read2_b32 v[140:141], v130 offset0:182 offset1:247
	s_add_u32 s24, s22, 0xd8400
	s_addc_u32 s25, s23, 0
	s_waitcnt lgkmcnt(4)
	v_cvt_pk_bf16_f32 v156, v148, v149
	v_cvt_pk_bf16_f32 v157, v150, v151
	v_cvt_pk_bf16_f32 v158, v152, v153
	v_cvt_pk_bf16_f32 v159, v154, v155
	global_store_dwordx4 v132, v[156:159], s[24:25] nt
	ds_read2_b32 v[148:149], v129 offset0:56 offset1:121
	ds_read2_b32 v[150:151], v129 offset0:186 offset1:251
	ds_read2_b32 v[152:153], v130 offset0:60 offset1:125
	ds_read2_b32 v[154:155], v130 offset0:190 offset1:255
	s_add_u32 s24, s22, 0x103800
	s_addc_u32 s25, s23, 0
	s_waitcnt lgkmcnt(4)
	v_cvt_pk_bf16_f32 v142, v134, v135
	v_cvt_pk_bf16_f32 v143, v136, v137
	v_cvt_pk_bf16_f32 v144, v138, v139
	v_cvt_pk_bf16_f32 v145, v140, v141
	global_store_dwordx4 v132, v[142:145], s[24:25] nt
	s_add_u32 s24, s22, 0x12ec00
	s_addc_u32 s25, s23, 0
	s_waitcnt lgkmcnt(0)
	v_cvt_pk_bf16_f32 v156, v148, v149
	v_cvt_pk_bf16_f32 v157, v150, v151
	v_cvt_pk_bf16_f32 v158, v152, v153
	v_cvt_pk_bf16_f32 v159, v154, v155
	global_store_dwordx4 v132, v[156:159], s[24:25] nt
	s_add_u32 s22, s22, 0x400
	s_addc_u32 s23, s23, 0
	s_add_i32 s26, s26, 1
	s_cmp_ge_u32 s26, 21
	s_cbranch_scc1 .Lhn_fin
	s_cmp_eq_u32 s26, 1
	s_cbranch_scc0 .Lhn_w1
	s_waitcnt vmcnt(24)
.Lhn_w1:
	s_waitcnt vmcnt(32)
	ds_write2_b32 v128, v64, v65 offset1:1
	ds_write2_b32 v128, v66, v67 offset0:2 offset1:3
	v_add_u32_e32 v133, 0x410, v128
	ds_write2_b32 v133, v68, v69 offset1:1
	ds_write2_b32 v133, v70, v71 offset0:2 offset1:3
	v_add_u32_e32 v147, 0x820, v128
	ds_write2_b32 v147, v72, v73 offset1:1
	ds_write2_b32 v147, v74, v75 offset0:2 offset1:3
	v_add_u32_e32 v133, 0xc30, v128
	ds_write2_b32 v133, v76, v77 offset1:1
	ds_write2_b32 v133, v78, v79 offset0:2 offset1:3
	v_add_u32_e32 v147, 0x1040, v128
	ds_write2_b32 v147, v80, v81 offset1:1
	ds_write2_b32 v147, v82, v83 offset0:2 offset1:3
	v_add_u32_e32 v133, 0x1450, v128
	ds_write2_b32 v133, v84, v85 offset1:1
	ds_write2_b32 v133, v86, v87 offset0:2 offset1:3
	v_add_u32_e32 v147, 0x1860, v128
	ds_write2_b32 v147, v88, v89 offset1:1
	ds_write2_b32 v147, v90, v91 offset0:2 offset1:3
	v_add_u32_e32 v133, 0x1c70, v128
	ds_write2_b32 v133, v92, v93 offset1:1
	ds_write2_b32 v133, v94, v95 offset0:2 offset1:3
	v_add_u32_e32 v147, 0x2080, v128
	ds_write2_b32 v147, v96, v97 offset1:1
	ds_write2_b32 v147, v98, v99 offset0:2 offset1:3
	v_add_u32_e32 v133, 0x2490, v128
	ds_write2_b32 v133, v100, v101 offset1:1
	ds_write2_b32 v133, v102, v103 offset0:2 offset1:3
	v_add_u32_e32 v147, 0x28a0, v128
	ds_write2_b32 v147, v104, v105 offset1:1
	ds_write2_b32 v147, v106, v107 offset0:2 offset1:3
	v_add_u32_e32 v133, 0x2cb0, v128
	ds_write2_b32 v133, v108, v109 offset1:1
	ds_write2_b32 v133, v110, v111 offset0:2 offset1:3
	v_add_u32_e32 v147, 0x30c0, v128
	ds_write2_b32 v147, v112, v113 offset1:1
	ds_write2_b32 v147, v114, v115 offset0:2 offset1:3
	v_add_u32_e32 v133, 0x34d0, v128
	ds_write2_b32 v133, v116, v117 offset1:1
	ds_write2_b32 v133, v118, v119 offset0:2 offset1:3
	v_add_u32_e32 v147, 0x38e0, v128
	ds_write2_b32 v147, v120, v121 offset1:1
	ds_write2_b32 v147, v122, v123 offset0:2 offset1:3
	v_add_u32_e32 v133, 0x3cf0, v128
	ds_write2_b32 v133, v124, v125 offset1:1
	ds_write2_b32 v133, v126, v127 offset0:2 offset1:3
	s_waitcnt lgkmcnt(0)
; #define LAS __attribute__((address_space(3)))
; __device__ __forceinline__ unsigned pk2(float lo, float hi) { return pg8::cvt_pk_bf16(lo, hi); }
; __device__ __forceinline__ void p0_load(const float* W, int N, int k0, int n0, int lane, f32x4 (&v)[16]) {
;     const int c = lane & 15, rq = lane >> 4;
;     int col = n0 + 4 * c; col = col < N - 4 ? col : N - 4;
;     const float* p = W + (size_t)(k0 + rq) * N + col;
; #pragma unroll
;     for (int j = 0; j < 16; ++j) v[j] = __builtin_nontemporal_load((const f32x4*)(p + (size_t)(4 * j) * N));
; }
; __device__ __forceinline__ void p0_finish(bf16* WT, const float* gain, int N, int k0, int n0, int ldw, int blk, int off, int lane, const f32x4 (&v)[16], LAS float* scr) {
;     const int c = lane & 15, rq = lane >> 4, c8 = lane & 7;
;     f32x4 g0 = {1.f, 1.f, 1.f, 1.f}, g1 = g0;
;     if (gain) { g0 = *(const f32x4*)(gain + k0 + 8 * c8); g1 = *(const f32x4*)(gain + k0 + 8 * c8 + 4); }
; #pragma unroll
;     for (int j = 0; j < 16; ++j) { LAS float* s = scr + (4 * j + rq) * 65 + 4 * c; s[0] = v[j][0]; s[1] = v[j][1]; s[2] = v[j][2]; s[3] = v[j][3]; }
;     asm volatile("s_waitcnt lgkmcnt(0)" ::: "memory");
; #pragma unroll
;     for (int jj = 0; jj < 8; ++jj) { const int n = (lane >> 3) + 8 * jj; const LAS float* s = scr + (8 * c8) * 65 + n;
;         u32x4 o; o.x = pk2(s[0 * 65] * g0[0], s[1 * 65] * g0[1]); o.y = pk2(s[2 * 65] * g0[2], s[3 * 65] * g0[3]); o.z = pk2(s[4 * 65] * g1[0], s[5 * 65] * g1[1]); o.w = pk2(s[6 * 65] * g1[2], s[7 * 65] * g1[3]);
;         const int ng = n0 + n;
;         if (ng < N) { const int row = (ng >> 7) * blk + (ng & 127) + off; __builtin_nontemporal_store(o, (u32x4*)(WT + (size_t)row * ldw + k0 + 8 * c8)); } }
;     asm volatile("s_waitcnt lgkmcnt(0)" ::: "memory");
; }
	s_cmp_lt_u32 s27, 21
	s_cselect_b32 s2, 0x800000, 0
	s_add_u32 s20, s20, s2
	s_addc_u32 s21, s21, 0
	s_add_i32 s27, s27, 1
	global_load_dwordx4 v[64:67], v131, s[20:21] nt
	s_add_u32 s24, s20, 0x10000
	s_addc_u32 s25, s21, 0
	global_load_dwordx4 v[68:71], v131, s[24:25] nt
	s_add_u32 s24, s20, 0x20000
	s_addc_u32 s25, s21, 0
	global_load_dwordx4 v[72:75], v131, s[24:25] nt
	s_add_u32 s24, s20, 0x30000
	s_addc_u32 s25, s21, 0
	global_load_dwordx4 v[76:79], v131, s[24:25] nt
	s_add_u32 s24, s20, 0x40000
	s_addc_u32 s25, s21, 0
	global_load_dwordx4 v[80:83], v131, s[24:25] nt
	s_add_u32 s24, s20, 0x50000
	s_addc_u32 s25, s21, 0
	global_load_dwordx4 v[84:87], v131, s[24:25] nt
	s_add_u32 s24, s20, 0x60000
	s_addc_u32 s25, s21, 0
	global_load_dwordx4 v[88:91], v131, s[24:25] nt
	s_add_u32 s24, s20, 0x70000
	s_addc_u32 s25, s21, 0
	global_load_dwordx4 v[92:95], v131, s[24:25] nt
	s_add_u32 s24, s20, 0x80000
	s_addc_u32 s25, s21, 0
	global_load_dwordx4 v[96:99], v131, s[24:25] nt
	s_add_u32 s24, s20, 0x90000
	s_addc_u32 s25, s21, 0
	global_load_dwordx4 v[100:103], v131, s[24:25] nt
	s_add_u32 s24, s20, 0xa0000
	s_addc_u32 s25, s21, 0
	global_load_dwordx4 v[104:107], v131, s[24:25] nt
	s_add_u32 s24, s20, 0xb0000
	s_addc_u32 s25, s21, 0
	global_load_dwordx4 v[108:111], v131, s[24:25] nt
	s_add_u32 s24, s20, 0xc0000
	s_addc_u32 s25, s21, 0
	global_load_dwordx4 v[112:115], v131, s[24:25] nt
	s_add_u32 s24, s20, 0xd0000
	s_addc_u32 s25, s21, 0
	global_load_dwordx4 v[116:119], v131, s[24:25] nt
	s_add_u32 s24, s20, 0xe0000
	s_addc_u32 s25, s21, 0
	global_load_dwordx4 v[120:123], v131, s[24:25] nt
	s_add_u32 s24, s20, 0xf0000
	s_addc_u32 s25, s21, 0
	global_load_dwordx4 v[124:127], v131, s[24:25] nt
	ds_read2_b32 v[134:135], v129 offset0:0 offset1:65
	ds_read2_b32 v[136:137], v129 offset0:130 offset1:195
	ds_read2_b32 v[138:139], v130 offset0:4 offset1:69
	ds_read2_b32 v[140:141], v130 offset0:134 offset1:199
	ds_read2_b32 v[148:149], v129 offset0:8 offset1:73
	ds_read2_b32 v[150:151], v129 offset0:138 offset1:203
	ds_read2_b32 v[152:153], v130 offset0:12 offset1:77
	ds_read2_b32 v[154:155], v130 offset0:142 offset1:207
	s_mov_b64 s[24:25], s[22:23]
	s_waitcnt lgkmcnt(4)
	v_cvt_pk_bf16_f32 v142, v134, v135
	v_cvt_pk_bf16_f32 v143, v136, v137
	v_cvt_pk_bf16_f32 v144, v138, v139
	v_cvt_pk_bf16_f32 v145, v140, v141
	global_store_dwordx4 v132, v[142:145], s[24:25] nt
	ds_read2_b32 v[134:135], v129 offset0:16 offset1:81
	ds_read2_b32 v[136:137], v129 offset0:146 offset1:211
	ds_read2_b32 v[138:139], v130 offset0:20 offset1:85
	ds_read2_b32 v[140:141], v130 offset0:150 offset1:215
	s_add_u32 s24, s22, 0x2b400
	s_addc_u32 s25, s23, 0
	s_waitcnt lgkmcnt(4)
	v_cvt_pk_bf16_f32 v156, v148, v149
	v_cvt_pk_bf16_f32 v157, v150, v151
	v_cvt_pk_bf16_f32 v158, v152, v153
	v_cvt_pk_bf16_f32 v159, v154, v155
	global_store_dwordx4 v132, v[156:159], s[24:25] nt
	ds_read2_b32 v[148:149], v129 offset0:24 offset1:89
	ds_read2_b32 v[150:151], v129 offset0:154 offset1:219
	ds_read2_b32 v[152:153], v130 offset0:28 offset1:93
	ds_read2_b32 v[154:155], v130 offset0:158 offset1:223
	s_add_u32 s24, s22, 0x56800
	s_addc_u32 s25, s23, 0
	s_waitcnt lgkmcnt(4)
	v_cvt_pk_bf16_f32 v142, v134, v135
	v_cvt_pk_bf16_f32 v143, v136, v137
	v_cvt_pk_bf16_f32 v144, v138, v139
	v_cvt_pk_bf16_f32 v145, v140, v141
	global_store_dwordx4 v132, v[142:145], s[24:25] nt
	ds_read2_b32 v[134:135], v129 offset0:32 offset1:97
	ds_read2_b32 v[136:137], v129 offset0:162 offset1:227
	ds_read2_b32 v[138:139], v130 offset0:36 offset1:101
	ds_read2_b32 v[140:141], v130 offset0:166 offset1:231
	s_add_u32 s24, s22, 0x81c00
	s_addc_u32 s25, s23, 0
	s_waitcnt lgkmcnt(4)
	v_cvt_pk_bf16_f32 v156, v148, v149
	v_cvt_pk_bf16_f32 v157, v150, v151
	v_cvt_pk_bf16_f32 v158, v152, v153
	v_cvt_pk_bf16_f32 v159, v154, v155
	global_store_dwordx4 v132, v[156:159], s[24:25] nt
	ds_read2_b32 v[148:149], v129 offset0:40 offset1:105
	ds_read2_b32 v[150:151], v129 offset0:170 offset1:235
	ds_read2_b32 v[152:153], v130 offset0:44 offset1:109
	ds_read2_b32 v[154:155], v130 offset0:174 offset1:239
	s_add_u32 s24, s22, 0xad000
	s_addc_u32 s25, s23, 0
	s_waitcnt lgkmcnt(4)
	v_cvt_pk_bf16_f32 v142, v134, v135
	v_cvt_pk_bf16_f32 v143, v136, v137
	v_cvt_pk_bf16_f32 v144, v138, v139
	v_cvt_pk_bf16_f32 v145, v140, v141
	global_store_dwordx4 v132, v[142:145], s[24:25] nt
	ds_read2_b32 v[134:135], v129 offset0:48 offset1:113
	ds_read2_b32 v[136:137], v129 offset0:178 offset1:243
	ds_read2_b32 v[138:139], v130 offset0:52 offset1:117
	ds_read2_b32 v[140:141], v130 offset0:182 offset1:247
	s_add_u32 s24, s22, 0xd8400
	s_addc_u32 s25, s23, 0
	s_waitcnt lgkmcnt(4)
	v_cvt_pk_bf16_f32 v156, v148, v149
	v_cvt_pk_bf16_f32 v157, v150, v151
	v_cvt_pk_bf16_f32 v158, v152, v153
	v_cvt_pk_bf16_f32 v159, v154, v155
	global_store_dwordx4 v132, v[156:159], s[24:25] nt
	ds_read2_b32 v[148:149], v129 offset0:56 offset1:121
	ds_read2_b32 v[150:151], v129 offset0:186 offset1:251
	ds_read2_b32 v[152:153], v130 offset0:60 offset1:125
	ds_read2_b32 v[154:155], v130 offset0:190 offset1:255
	s_add_u32 s24, s22, 0x103800
	s_addc_u32 s25, s23, 0
	s_waitcnt lgkmcnt(4)
	v_cvt_pk_bf16_f32 v142, v134, v135
	v_cvt_pk_bf16_f32 v143, v136, v137
	v_cvt_pk_bf16_f32 v144, v138, v139
	v_cvt_pk_bf16_f32 v145, v140, v141
	global_store_dwordx4 v132, v[142:145], s[24:25] nt
	s_add_u32 s24, s22, 0x12ec00
	s_addc_u32 s25, s23, 0
	s_waitcnt lgkmcnt(0)
	v_cvt_pk_bf16_f32 v156, v148, v149
	v_cvt_pk_bf16_f32 v157, v150, v151
	v_cvt_pk_bf16_f32 v158, v152, v153
	v_cvt_pk_bf16_f32 v159, v154, v155
	global_store_dwordx4 v132, v[156:159], s[24:25] nt
	s_add_u32 s22, s22, 0x400
	s_addc_u32 s23, s23, 0
	s_add_i32 s26, s26, 1
	s_cmp_lt_u32 s26, 21
	s_cbranch_scc1 .Lhn_loop

;     __host__ __device__ bool next(int i, Unit& u) const { return map((long)i * G + c, u); }
; template <class Epi, class Sched, bool ALIGN_EPI = false, bool SP2 = false>
; __device__ __forceinline__ void gemm_phase(PG8_LAS unsigned char* lds, const Gemm g, const Sched& S, const Epi& E, int wid) {
;     const int lane = fresh_lane(), tid = wid * 64 + lane, wr = wid >> 2, wc = wid & 3, fr = lane & 15, fq = lane >> 4;
;     const int K = g.K, nt = K / BK;
;     unsigned voffA[2], voffB[2];
; #pragma unroll
;     for (int i = 0; i < 2; ++i) { int R, C; stage_rc(tid * 16 + i * 8192, R, C); const int Rb = Epi::PERM ? ((R & ~31) + perm32(R & 31)) : R;
;         voffA[i] = (unsigned)(R * g.lda + C) * 2u; voffB[i] = (unsigned)(Rb * g.ldb + C) * 2u; }
;     const size_t kstep = (size_t)(BK * 2);
;     const size_t hstepA = (size_t)HALF * g.lda * 2, hstepB = (size_t)HALF * g.ldb * 2;
;     const size_t tstepA = 2 * hstepA, tstepB = 2 * hstepB;
;     const unsigned ldsw = (unsigned)wid * 1024u;
;     const int aoff = lds_byte(wr * 64 + fr, fq * 8), boff = lds_byte(wc * 32 + fr, fq * 8);
;     ...
;     Unit cur, nxt; int ui = 0;
;     if (!S.next(0, cur)) return;
;     f32x4 acc[2][2][4][2];
; #pragma unroll
;     for (int a = 0; a < 2; ++a)
; #pragma unroll
;         for (int b = 0; b < 2; ++b)
; #pragma unroll
;             for (int m = 0; m < 4; ++m)
; #pragma unroll
;                 for (int n = 0; n < 2; ++n) acc[a][b][m][n] = (f32x4){0.f, 0.f, 0.f, 0.f};
;     bf16x8 At[4][2], B0[2][2], B1[2][2];
;     const char* cA = (const char*)g.A + (size_t)cur.pm * tstepA; const char* cB = (const char*)g.Bt + (size_t)cur.pn * tstepB;
;     S.a_ready(cur);
;     if constexpr (SP2) {
;         PG8_STAGE_NT(PG8_SB(0, 0), cB, voffB); PG8_STAGE_NT(PG8_SB(0, 1), cB + hstepB, voffB); PG8_STAGE(PG8_SA(0, 0), cA, voffA); PG8_STAGE(PG8_SA(0, 1), cA + hstepA, voffA);
;         if (wr == 1) PG8_BAR;
;         PG8_WAIT_V(2); PG8_BAR;
;         PG8_STAGE_NT(PG8_SB(1, 0), cB + kstep, voffB); PG8_STAGE(PG8_SA(1, 0), cA + kstep, voffA); PG8_STAGE_NT(PG8_SB(1, 1), cB + hstepB + kstep, voffB);
;         PG8_WAIT_V(6); PG8_BAR;
;     } else {
;         PG8_STAGE_NT(PG8_SB(0, 0), cB, voffB); PG8_STAGE(PG8_SA(0, 0), cA, voffA); PG8_STAGE_NT(PG8_SB(0, 1), cB + hstepB, voffB); PG8_STAGE(PG8_SA(0, 1), cA + hstepA, voffA);
;         if (wr == 1) PG8_BAR;
;         PG8_WAIT_V(4); PG8_BAR;
.Lhn_done:
	s_cmpk_gt_i32 s8, 0xabf
	v_mbcnt_lo_u32_b32 v0, -1, 0
	v_mbcnt_hi_u32_b32 v0, -1, v0
	s_waitcnt vmcnt(15)
	v_mbcnt_lo_u32_b32 v10, -1, 0
	v_mbcnt_hi_u32_b32 v10, -1, v10
	s_cbranch_scc1 .LBB0_1140
	s_lshl_b32 s9, s28, 10
	v_lshl_add_u32 v0, v10, 4, s9
	s_waitcnt lgkmcnt(0)
	v_add_u32_e32 v1, 0x2000, v0
	v_ashrrev_i32_e32 v2, 31, v1
	v_lshrrev_b32_e32 v2, 22, v2
	v_add_u32_e32 v2, v1, v2
	v_ashrrev_i32_e32 v8, 10, v2
	v_mul_i32_i24_e32 v2, 0x400, v8
	v_sub_u32_e32 v1, v1, v2
	v_lshrrev_b32_e32 v2, 4, v1
	v_bitop3_b32 v1, v2, v1, 32 bitop3:0x6c
	v_ashrrev_i32_e32 v2, 31, v1
	v_lshrrev_b32_e32 v2, 26, v2
	v_add_u32_e32 v2, v1, v2
	v_ashrrev_i32_e32 v9, 6, v2
	v_lshlrev_b32_e32 v3, 3, v8
	v_and_b32_e32 v2, 0xffc0, v2
	v_and_b32_e32 v3, -16, v3
	v_sub_u32_e32 v1, v1, v2
	v_add_u32_e32 v3, v9, v3
	v_lshrrev_b16_e32 v2, 7, v1
	v_and_b32_e32 v4, 3, v9
	s_mov_b32 s4, 0x3ffffe0
	v_lshrrev_b32_e32 v5, 2, v3
	v_lshlrev_b32_e32 v6, 1, v3
	v_and_b32_e32 v2, 1, v2
	v_and_or_b32 v4, v3, s4, v4
	v_and_b32_e32 v5, 4, v5
	v_and_b32_e32 v6, 24, v6
	v_add_u16_e32 v1, v1, v2
	v_mov_b32_e32 v2, 1
	v_or3_b32 v4, v4, v5, v6
	v_lshlrev_b32_e32 v5, 5, v8
	v_ashrrev_i16_sdwa v1, v2, sext(v1) dst_sel:DWORD dst_unused:UNUSED_PAD src0_sel:DWORD src1_sel:BYTE_0
	s_movk_i32 s2, 0x1040
	v_and_b32_e32 v11, 32, v5
	s_waitcnt vmcnt(14)
	v_bfe_i32 v12, v1, 0, 16
	v_mul_lo_u32 v4, v4, s2
	v_add_u32_e32 v1, v11, v12
	v_mul_lo_u32 v3, v3, s2
	v_add_lshl_u32 v128, v4, v1, 1
	v_add_lshl_u32 v130, v1, v3, 1
	v_ashrrev_i32_e32 v1, 31, v0
	v_lshrrev_b32_e32 v1, 22, v1
	v_add_u32_e32 v1, v0, v1
	v_ashrrev_i32_e32 v13, 10, v1
	v_mul_i32_i24_e32 v1, 0x400, v13
	v_sub_u32_e32 v0, v0, v1
	v_lshrrev_b32_e32 v1, 4, v0
	v_bitop3_b32 v0, v1, v0, 32 bitop3:0x6c
	v_ashrrev_i32_e32 v1, 31, v0
	v_lshrrev_b32_e32 v1, 26, v1
	v_add_u32_e32 v1, v0, v1
	v_lshlrev_b32_e32 v3, 3, v13
	v_ashrrev_i32_e32 v14, 6, v1
	v_and_b32_e32 v3, -16, v3
	v_add_u32_e32 v3, v14, v3
	v_and_b32_e32 v4, 3, v14
	s_ashr_i32 s17, s8, 31
	v_and_or_b32 v4, v3, s4, v4
	s_lshr_b32 s4, s17, 29
	s_add_i32 s4, s8, s4
	s_ashr_i32 s5, s4, 3
	s_and_b32 s4, s4, -8
	s_lshr_b32 s3, s95, 8
	s_sub_i32 s4, s8, s4
	s_cmp_lt_i32 s4, 0
	s_movk_i32 s19, 0x159
	s_cselect_b32 s6, s19, 0x158
	s_mul_i32 s4, s4, s6
	s_add_i32 s4, s4, s5
	s_mul_hi_i32 s5, s4, 0x2fa0be83
	s_lshr_b32 s6, s5, 31
	s_ashr_i32 s5, s5, 7
	s_add_i32 s5, s5, s6
	s_lshl_b32 s6, s5, 3
	s_mulk_i32 s5, 0x2b0
	s_sub_i32 s5, s4, s5
	s_sext_i32_i16 s4, s5
	s_bfe_u32 s4, s4, 0x3001c
	s_add_i32 s7, s5, s4
	s_sext_i32_i16 s21, s7
	s_and_b32 s7, s7, 0xfff8
	s_sub_i32 s5, s5, s7
	v_lshrrev_b32_e32 v5, 2, v3
	v_lshlrev_b32_e32 v6, 1, v3
	v_and_b32_e32 v1, 0xc0, v1
	s_sext_i32_i16 s5, s5
	v_and_b32_e32 v5, 4, v5
	v_and_b32_e32 v6, 24, v6
	v_sub_u32_e32 v0, v0, v1
	s_add_i32 s20, s6, s5
	s_ashr_i32 s6, s21, 3
	v_or3_b32 v4, v4, v5, v6
	v_lshlrev_b32_e32 v5, 5, v13
	v_ashrrev_i16_sdwa v0, v2, sext(v0) dst_sel:DWORD dst_unused:UNUSED_PAD src0_sel:DWORD src1_sel:BYTE_0
	s_lshr_b32 s4, s21, 3
	s_mul_hi_i32 s7, s6, 0x208000
	s_mul_i32 s6, s6, 0x208000
	v_and_b32_e32 v15, 32, v5
	s_waitcnt vmcnt(12)
	v_bfe_i32 v16, v0, 0, 16
	s_add_u32 s48, s36, s6
	v_mul_lo_u32 v4, v4, s2
	v_add_u32_e32 v0, v15, v16
	s_addc_u32 s49, s37, s7
	s_add_i32 s22, s9, 0
	v_add_lshl_u32 v132, v4, v0, 1
	s_add_i32 m0, s22, 0x10000
	s_mul_i32 s23, s20, 0x208000
	global_load_lds_dwordx4 v132, s[48:49]
	s_add_i32 m0, s22, 0x12000
	s_add_u32 s6, s48, 0x104000
	global_load_lds_dwordx4 v128, s[48:49]
	s_addc_u32 s7, s49, 0
	s_add_i32 m0, s22, 0x14000
	s_mul_hi_i32 s5, s20, 0x208000
	global_load_lds_dwordx4 v132, s[6:7]
	s_add_i32 m0, s22, 0x16000
	s_add_u32 s46, s26, s23
	v_mul_lo_u32 v1, v3, s2
	s_addc_u32 s47, s27, s5
	s_add_i32 s23, s22, 0x2000
	v_add_lshl_u32 v134, v0, v1, 1
	global_load_lds_dwordx4 v128, s[6:7]
	s_mov_b32 m0, s22
	s_add_u32 s6, s46, 0x104000
	global_load_lds_dwordx4 v134, s[46:47]
	s_mov_b32 m0, s23
	s_addc_u32 s7, s47, 0
	s_add_i32 s24, s22, 0x4000
	global_load_lds_dwordx4 v130, s[46:47]
	s_mov_b32 m0, s24
	s_add_i32 s25, s22, 0x6000
	global_load_lds_dwordx4 v134, s[6:7]
	s_mov_b32 m0, s25
	s_waitcnt vmcnt(0)
	v_mov_b32_e32 v133, 0
	global_load_lds_dwordx4 v130, s[6:7]
	v_mov_b32_e32 v129, v133
	v_mov_b32_e32 v135, v133
	v_mov_b32_e32 v131, v133
	s_cmp_eq_u32 s3, 1
	s_mov_b32 s29, 0
	v_lshl_add_u64 v[6:7], s[48:49], 0, v[132:133]
	v_lshl_add_u64 v[4:5], s[48:49], 0, v[128:129]
	v_lshl_add_u64 v[0:1], s[46:47], 0, v[134:135]
	s_cselect_b64 s[6:7], -1, 0
	s_cmp_lg_u32 s3, 1
	v_lshl_add_u64 v[2:3], s[46:47], 0, v[130:131]
	s_cbranch_scc1 .LBB0_1123
	s_barrier
